# workgroup stagger stubs now test bits of the true block index (kept in a VGPR lane) instead of an SGPR that later phases reuse
# speedup vs baseline: 1.0128x; 1.0050x over previous
;   DI bf16_t* h() const { return (bf16_t*)(ws + OFF_H); }
; DI void phase_gemm_out(const Params& p, char* smem, const bf16_t* Wt, const float* R, float* O) {
;   u32x4 ra[4], rb[4]; bool pre = false;
;   for (int t = blockIdx.x; t < 64 * 8; t += gridDim.x) {
;     const int mt = t & 63, nt = t >> 6, tn = t + gridDim.x;
;     const bool has_next = tn < 64 * 8;
;     const GTile tl{p.h(), D, Wt, D, D, mt * 256, nt * 256}, nx{p.h(), D, Wt, D, D, (tn & 63) * 256, (tn >> 6) * 256};
;     WAVE_GEOM;
;     f32x16 acc[2][4];
;     gemm_core<false>(tl, nx, has_next, has_next, pre, ra, rb, smem, acc);
.LBB0_742:
	s_or_b64 exec, exec, s[0:1]
	v_readlane_b32 s98, v252, 38
	s_bitcmp1_b32 s98, 6
	s_cbranch_scc0 .Lstag_6_0
	s_sleep 127
.Lstag_6_0:
	s_bitcmp1_b32 s98, 7
	s_cbranch_scc0 .Lstag_6_1
	s_sleep 127
	s_sleep 127

;   DI bf16_t* wt_in1() const { return (bf16_t*)(ws + OFF_WT_IN1); }
;   DI bf16_t* h() const { return (bf16_t*)(ws + OFF_H); }
; DI int in1_nt(int t) { return (t >> 6) < 23 ? (t >> 6) : 25; }
; DI void phase_gemm_in1(const Params& p, char* smem) {
;   u32x4 ra[4], rb[4]; bool pre = false;
;   for (int t = blockIdx.x; t < 64 * 24; t += gridDim.x) {
;     const int mt = t & 63, nt = in1_nt(t), tn = t + gridDim.x;
;     const bool has_next = tn < 64 * 24;
;     const GTile tl{p.h(), D, p.wt_in1(), D, D, mt * 256, nt * 256}, nx{p.h(), D, p.wt_in1(), D, D, (tn & 63) * 256, in1_nt(tn) * 256};
.LBB0_874:
	s_or_b64 exec, exec, s[0:1]
	v_readlane_b32 s98, v252, 38
	s_bitcmp1_b32 s98, 6
	s_cbranch_scc0 .Lstag_8_0
	s_sleep 64
.Lstag_8_0:
	s_bitcmp1_b32 s98, 7
	s_cbranch_scc0 .Lstag_8_1
	s_sleep 127

; DI void phase_attn1(const Params& p, char* smem) {
;   const int G = gridDim.x;
;   for (int round = 0; round * G < 512; ++round) {
;     const int j = (round & 1) ? (G - 1 - (int)blockIdx.x) : (int)blockIdx.x;
;     const int t = round * G + j;
;     if (t >= 512) continue;
;     const int qt = 15 - (t >> 5), bh = t & 31;
;     mla_item(p, bh >> 3, bh & 7, qt, smem);
;   }
.LBB0_1361:
	s_or_b64 exec, exec, s[0:1]
	s_not_b32 s0, s84
	s_add_i32 s27, s96, s0
	s_add_u32 s24, s22, 0x154c0000
	s_addc_u32 s25, s23, 0
	s_add_u32 s33, s22, 0x184c0000
	s_addc_u32 s40, s23, 0
	s_add_u32 s41, s22, 0x1a4c0000
	s_addc_u32 s44, s23, 0
	s_add_u32 s45, s22, 0x1a6c0000
	s_addc_u32 s46, s23, 0
	s_add_u32 s28, s22, 0x40c0000
	s_movk_i32 s34, 0xff00
	s_addc_u32 s29, s23, 0
	s_mov_b32 s31, 0
	s_movk_i32 s47, 0xc00
	v_mov_b32_e32 v0, 0
	s_mov_b32 s48, 0x2aaaaaab
	s_mov_b32 s35, -1
	s_movk_i32 s49, 0x190
	s_movk_i32 s50, 0x88
	s_movk_i32 s51, 0x6400
	s_mov_b32 s52, 0xf149f2ca
	s_mov_b32 s53, 0x3dd53b94
	s_mov_b32 s54, 0x41000000
	s_mov_b64 s[36:37], 0x20000
	s_mov_b64 s[38:39], 0x2000
	s_movk_i32 s55, 0x3300
	s_mov_b64 s[42:43], 0x80c0a00
	s_mov_b32 s56, 0x80c0000
	v_mov_b32_e32 v199, 0xf149f2ca
	v_mbcnt_hi_u32_b32 v198, -1, v207
	s_mov_b32 s0, 0
	s_mov_b32 s57, 0
	v_readlane_b32 s98, v252, 38
	s_bitcmp1_b32 s98, 6
	s_cbranch_scc0 .Lstag_10
	s_sleep 127
